# v29 + conversion-phase stores written through (sc1) and the grid barrier's L2 write-back dropped
# baseline (speedup 1.0000x reference)
.LBB0_18:
	v_add_co_u32_e32 v2, vcc, 0xffffd000, v56
	v_lshl_add_u64 v[4:5], v[56:57], 0, s[24:25]
	s_nop 0
	v_addc_co_u32_e32 v3, vcc, -1, v57, vcc
	global_load_dwordx4 v[60:63], v[2:3], off offset:-2064 nt
	global_load_dwordx4 v[70:73], v[4:5], off offset:16 nt
	global_load_dwordx4 v[74:77], v[2:3], off offset:-16 nt
	v_lshl_add_u64 v[2:3], v[56:57], 0, s[26:27]
	global_load_dwordx4 v[78:81], v[2:3], off offset:16 nt
	v_add_co_u32_e32 v20, vcc, s13, v56
	s_waitcnt lgkmcnt(0)
	v_lshl_add_u64 v[18:19], v[56:57], 0, s[28:29]
	v_addc_co_u32_e32 v21, vcc, -1, v57, vcc
	v_lshl_add_u64 v[22:23], v[56:57], 0, s[30:31]
	v_lshl_add_u64 v[24:25], v[56:57], 0, s[34:35]
	v_add_co_u32_e32 v58, vcc, s15, v56
	v_mov_b32_e32 v88, 0
	s_nop 0
	v_addc_co_u32_e32 v59, vcc, -1, v57, vcc
	global_load_dwordx4 v[2:5], v[56:57], off offset:-2048 nt
	global_load_dwordx4 v[6:9], v[56:57], off offset:-2064 nt
	global_load_dwordx4 v[10:13], v[56:57], off nt
	global_load_dwordx4 v[14:17], v[56:57], off offset:-16 nt
	global_load_dwordx4 v[46:49], v[20:21], off offset:-2064 nt
	global_load_dwordx4 v[42:45], v[18:19], off offset:16 nt
	global_load_dwordx4 v[38:41], v[20:21], off offset:-16 nt
	global_load_dwordx4 v[34:37], v[22:23], off offset:16 nt
	global_load_dwordx4 v[30:33], v[58:59], off offset:-2064 nt
	global_load_dwordx4 v[26:29], v[24:25], off offset:16 nt
	s_nop 0
	global_load_dwordx4 v[22:25], v[58:59], off offset:-16 nt
	global_load_dwordx4 v[18:21], v[56:57], off offset:-4096 nt
	s_waitcnt vmcnt(15)
	v_cvt_pk_bf16_f32 v82, v60, v61
	v_mov_b32_e32 v89, 0
	v_lshl_add_u64 v[58:59], s[10:11], 0, v[54:55]
	v_add_co_u32_e32 v90, vcc, s43, v58
	v_lshl_add_u64 v[86:87], s[10:11], 0, v[52:53]
	s_nop 0
	v_addc_co_u32_e32 v91, vcc, 0, v59, vcc
	s_waitcnt vmcnt(14)
	v_mul_f32_e32 v85, v71, v71
	v_mul_f32_e32 v83, v61, v61
	v_mul_f32_e32 v84, v63, v63
	v_mul_f32_e32 v92, v73, v73
	s_waitcnt vmcnt(13)
	v_mul_f32_e32 v93, v75, v75
	v_mul_f32_e32 v94, v77, v77
	v_fmac_f32_e32 v83, v60, v60
	v_fmac_f32_e32 v84, v62, v62
	v_fmac_f32_e32 v85, v70, v70
	v_fmac_f32_e32 v92, v72, v72
	s_waitcnt vmcnt(12)
	v_mul_f32_e32 v95, v79, v79
	v_mul_f32_e32 v96, v81, v81
	v_fmac_f32_e32 v93, v74, v74
	v_fmac_f32_e32 v94, v76, v76
	v_add_f32_e32 v83, v83, v84
	v_add_f32_e32 v84, v85, v92
	v_fmac_f32_e32 v95, v78, v78
	v_fmac_f32_e32 v96, v80, v80
	v_add_f32_e32 v85, v93, v94
	v_add_f32_e32 v83, v83, v84
	v_add_f32_e32 v92, v95, v96
	v_add_f32_e32 v83, v83, v85
	v_add_f32_e32 v85, v83, v92
	ds_bpermute_b32 v92, v64, v85
	v_cvt_pk_fp8_f32 v88, v60, v61
	v_cvt_pk_bf16_f32 v83, v62, v63
	v_cvt_pk_bf16_f32 v84, v70, v71
	v_cvt_pk_fp8_f32 v89, v70, v71
	s_waitcnt lgkmcnt(0)
	v_add_f32_e32 v60, v85, v92
	ds_bpermute_b32 v61, v65, v60
	v_cvt_pk_fp8_f32 v88, v62, v63 op_sel:[0,0,1]
	v_cvt_pk_fp8_f32 v89, v72, v73 op_sel:[0,0,1]
	v_cvt_pk_bf16_f32 v85, v72, v73
	global_store_dwordx4 v[90:91], v[82:85], off offset:1024 sc1
	s_waitcnt lgkmcnt(0)
	v_add_f32_e32 v62, v60, v61
	ds_bpermute_b32 v63, v66, v62
	v_add_co_u32_e32 v60, vcc, s44, v86
	s_waitcnt lgkmcnt(0)
	v_add_f32_e32 v70, v62, v63
	ds_bpermute_b32 v71, v67, v70
	v_mov_b32_e32 v62, 0
	v_mov_b32_e32 v63, 0
	v_cvt_pk_fp8_f32 v62, v74, v75
	v_cvt_pk_fp8_f32 v63, v78, v79
	s_waitcnt lgkmcnt(0)
	v_add_f32_e32 v70, v70, v71
	ds_bpermute_b32 v71, v68, v70
	v_cvt_pk_fp8_f32 v62, v76, v77 op_sel:[0,0,1]
	v_cvt_pk_fp8_f32 v63, v80, v81 op_sel:[0,0,1]
	v_addc_co_u32_e32 v61, vcc, 0, v87, vcc
	s_waitcnt lgkmcnt(0)
	v_add_f32_e32 v70, v70, v71
	ds_bpermute_b32 v71, v69, v70
	global_store_dwordx2 v[60:61], v[88:89], off sc1
	v_cvt_pk_bf16_f32 v72, v74, v75
	v_cvt_pk_bf16_f32 v73, v76, v77
	v_cvt_pk_bf16_f32 v74, v78, v79
	v_cvt_pk_bf16_f32 v75, v80, v81
	global_store_dwordx4 v[90:91], v[72:75], off offset:2048 sc1
	global_store_dwordx2 v[60:61], v[62:63], off offset:512 sc1
	v_lshl_add_u64 v[62:63], s[10:11], 0, v[50:51]
	s_and_saveexec_b64 s[36:37], s[6:7]
	s_cbranch_execz .LBB0_20
	s_waitcnt lgkmcnt(0)
	v_add_f32_e32 v70, v70, v71
	v_cndmask_b32_e64 v72, 0, v70, s[4:5]
	v_add_co_u32_e32 v70, vcc, 0x100000, v62
	s_nop 1
	v_addc_co_u32_e32 v71, vcc, 0, v63, vcc
	global_store_dword v[70:71], v72, off sc1
.LBB0_20:
	s_or_b64 exec, exec, s[36:37]
	s_waitcnt vmcnt(11)
	v_mul_f32_e32 v70, v47, v47
	s_waitcnt lgkmcnt(0)
	v_mul_f32_e32 v71, v49, v49
	v_fmac_f32_e32 v70, v46, v46
	v_fmac_f32_e32 v71, v48, v48
	v_add_f32_e32 v70, v70, v71
	s_waitcnt vmcnt(10)
	v_mul_f32_e32 v71, v43, v43
	v_mul_f32_e32 v72, v45, v45
	v_fmac_f32_e32 v71, v42, v42
	v_fmac_f32_e32 v72, v44, v44
	v_add_f32_e32 v71, v71, v72
	v_add_f32_e32 v70, v70, v71
	s_waitcnt vmcnt(9)
	v_mul_f32_e32 v71, v39, v39
	v_mul_f32_e32 v72, v41, v41
	v_fmac_f32_e32 v71, v38, v38
	v_fmac_f32_e32 v72, v40, v40
	v_add_f32_e32 v71, v71, v72
	v_add_f32_e32 v70, v70, v71
	s_waitcnt vmcnt(8)
	v_mul_f32_e32 v71, v35, v35
	v_mul_f32_e32 v72, v37, v37
	v_fmac_f32_e32 v71, v34, v34
	v_fmac_f32_e32 v72, v36, v36
	v_add_f32_e32 v71, v71, v72
	v_add_f32_e32 v70, v70, v71
	ds_bpermute_b32 v71, v64, v70
	v_mov_b32_e32 v77, 0
	v_cvt_pk_fp8_f32 v77, v42, v43
	v_mov_b32_e32 v76, 0
	v_cvt_pk_bf16_f32 v72, v46, v47
	s_waitcnt lgkmcnt(0)
	v_add_f32_e32 v70, v70, v71
	ds_bpermute_b32 v71, v65, v70
	v_cvt_pk_bf16_f32 v73, v48, v49
	v_cvt_pk_fp8_f32 v76, v46, v47
	v_cvt_pk_bf16_f32 v74, v42, v43
	v_cvt_pk_bf16_f32 v75, v44, v45
	s_waitcnt lgkmcnt(0)
	v_add_f32_e32 v70, v70, v71
	ds_bpermute_b32 v71, v66, v70
	v_cvt_pk_fp8_f32 v77, v44, v45 op_sel:[0,0,1]
	v_mov_b32_e32 v44, 0
	v_mov_b32_e32 v45, 0
	v_cvt_pk_fp8_f32 v44, v38, v39
	s_waitcnt lgkmcnt(0)
	v_add_f32_e32 v70, v70, v71
	ds_bpermute_b32 v71, v67, v70
	v_cvt_pk_fp8_f32 v45, v34, v35
	v_cvt_pk_fp8_f32 v76, v48, v49 op_sel:[0,0,1]
	v_add_co_u32_e32 v42, vcc, s46, v58
	s_waitcnt lgkmcnt(0)
	v_add_f32_e32 v70, v70, v71
	ds_bpermute_b32 v71, v68, v70
	v_cvt_pk_fp8_f32 v44, v40, v41 op_sel:[0,0,1]
	v_cvt_pk_fp8_f32 v45, v36, v37 op_sel:[0,0,1]
	v_addc_co_u32_e32 v43, vcc, 0, v59, vcc
	s_waitcnt lgkmcnt(0)
	v_add_f32_e32 v70, v70, v71
	ds_bpermute_b32 v71, v69, v70
	global_store_dwordx4 v[42:43], v[72:75], off sc1
	global_store_dwordx2 v[60:61], v[76:77], off offset:1024 sc1
	v_cvt_pk_bf16_f32 v38, v38, v39
	v_cvt_pk_bf16_f32 v39, v40, v41
	v_cvt_pk_bf16_f32 v40, v34, v35
	v_cvt_pk_bf16_f32 v41, v36, v37
	global_store_dwordx4 v[42:43], v[38:41], off offset:1024 sc1
	global_store_dwordx2 v[60:61], v[44:45], off offset:1536 sc1
	s_and_saveexec_b64 s[36:37], s[6:7]
	s_cbranch_execz .LBB0_22
	s_waitcnt lgkmcnt(0)
	v_add_f32_e32 v34, v70, v71
	v_cndmask_b32_e64 v36, 0, v34, s[4:5]
	v_add_co_u32_e32 v34, vcc, 0x100000, v62
	s_nop 1
	v_addc_co_u32_e32 v35, vcc, 0, v63, vcc
	global_store_dword v[34:35], v36, off offset:64 sc1
.LBB0_22:
	s_or_b64 exec, exec, s[36:37]
	s_waitcnt vmcnt(11)
	v_mul_f32_e32 v34, v31, v31
	v_mul_f32_e32 v35, v33, v33
	v_fmac_f32_e32 v34, v30, v30
	v_fmac_f32_e32 v35, v32, v32
	v_add_f32_e32 v34, v34, v35
	s_waitcnt vmcnt(10)
	v_mul_f32_e32 v35, v27, v27
	v_mul_f32_e32 v36, v29, v29
	v_fmac_f32_e32 v35, v26, v26
	v_fmac_f32_e32 v36, v28, v28
	v_add_f32_e32 v35, v35, v36
	v_add_f32_e32 v34, v34, v35
	s_waitcnt vmcnt(9)
	v_mul_f32_e32 v35, v23, v23
	v_mul_f32_e32 v36, v25, v25
	v_fmac_f32_e32 v35, v22, v22
	v_fmac_f32_e32 v36, v24, v24
	v_add_f32_e32 v35, v35, v36
	v_add_f32_e32 v34, v34, v35
	s_waitcnt vmcnt(8)
	v_mul_f32_e32 v35, v19, v19
	v_mul_f32_e32 v36, v21, v21
	v_fmac_f32_e32 v35, v18, v18
	v_fmac_f32_e32 v36, v20, v20
	v_add_f32_e32 v35, v35, v36
	v_add_f32_e32 v34, v34, v35
	ds_bpermute_b32 v35, v64, v34
	v_mov_b32_e32 v40, 0
	v_mov_b32_e32 v41, 0
	v_cvt_pk_fp8_f32 v40, v30, v31
	v_cvt_pk_fp8_f32 v41, v26, v27
	s_waitcnt lgkmcnt(0)
	v_add_f32_e32 v34, v34, v35
	ds_bpermute_b32 v35, v65, v34
	v_cvt_pk_bf16_f32 v36, v30, v31
	v_mov_b32_e32 v30, 0
	v_mov_b32_e32 v31, 0
	v_cvt_pk_fp8_f32 v30, v22, v23
	s_waitcnt lgkmcnt(0)
	v_add_f32_e32 v34, v34, v35
	ds_bpermute_b32 v35, v66, v34
	v_cvt_pk_fp8_f32 v31, v18, v19
	v_cvt_pk_fp8_f32 v40, v32, v33 op_sel:[0,0,1]
	v_cvt_pk_fp8_f32 v41, v28, v29 op_sel:[0,0,1]
	v_cvt_pk_bf16_f32 v37, v32, v33
	s_waitcnt lgkmcnt(0)
	v_add_f32_e32 v34, v34, v35
	ds_bpermute_b32 v35, v67, v34
	v_cvt_pk_bf16_f32 v38, v26, v27
	v_add_co_u32_e32 v26, vcc, s47, v58
	v_cvt_pk_bf16_f32 v39, v28, v29
	s_waitcnt lgkmcnt(0)
	v_add_f32_e32 v34, v34, v35
	ds_bpermute_b32 v35, v68, v34
	v_addc_co_u32_e32 v27, vcc, 0, v59, vcc
	v_cvt_pk_fp8_f32 v30, v24, v25 op_sel:[0,0,1]
	v_cvt_pk_fp8_f32 v31, v20, v21 op_sel:[0,0,1]
	s_waitcnt lgkmcnt(0)
	v_add_f32_e32 v34, v34, v35
	ds_bpermute_b32 v35, v69, v34
	global_store_dwordx4 v[26:27], v[36:39], off offset:3072 sc1
	global_store_dwordx2 v[60:61], v[40:41], off offset:2048 sc1
	v_cvt_pk_bf16_f32 v26, v22, v23
	v_cvt_pk_bf16_f32 v27, v24, v25
	v_cvt_pk_bf16_f32 v28, v18, v19
	v_add_co_u32_e32 v18, vcc, 0x2208000, v58
	v_cvt_pk_bf16_f32 v29, v20, v21
	s_nop 1
	v_addc_co_u32_e32 v19, vcc, 0, v59, vcc
	global_store_dwordx4 v[18:19], v[26:29], off sc1
	global_store_dwordx2 v[60:61], v[30:31], off offset:2560 sc1
	s_and_saveexec_b64 s[36:37], s[6:7]
	s_cbranch_execz .LBB0_24
	s_waitcnt lgkmcnt(0)
	v_add_f32_e32 v18, v34, v35
	v_cndmask_b32_e64 v20, 0, v18, s[4:5]
	v_add_co_u32_e32 v18, vcc, 0x100000, v62
	s_nop 1
	v_addc_co_u32_e32 v19, vcc, 0, v63, vcc
	global_store_dword v[18:19], v20, off offset:128 sc1
.LBB0_24:
	s_or_b64 exec, exec, s[36:37]
	v_mul_f32_e32 v18, v7, v7
	v_mul_f32_e32 v19, v9, v9
	v_fmac_f32_e32 v18, v6, v6
	v_fmac_f32_e32 v19, v8, v8
	v_add_f32_e32 v18, v18, v19
	v_mul_f32_e32 v19, v3, v3
	v_mul_f32_e32 v20, v5, v5
	v_fmac_f32_e32 v19, v2, v2
	v_fmac_f32_e32 v20, v4, v4
	v_add_f32_e32 v19, v19, v20
	v_add_f32_e32 v18, v18, v19
	v_mul_f32_e32 v19, v15, v15
	v_mul_f32_e32 v20, v17, v17
	v_fmac_f32_e32 v19, v14, v14
	v_fmac_f32_e32 v20, v16, v16
	v_add_f32_e32 v19, v19, v20
	v_add_f32_e32 v18, v18, v19
	v_mul_f32_e32 v19, v11, v11
	v_mul_f32_e32 v20, v13, v13
	v_fmac_f32_e32 v19, v10, v10
	v_fmac_f32_e32 v20, v12, v12
	v_add_f32_e32 v19, v19, v20
	v_add_f32_e32 v18, v18, v19
	ds_bpermute_b32 v19, v64, v18
	v_mov_b32_e32 v24, 0
	v_cvt_pk_fp8_f32 v24, v6, v7
	v_mov_b32_e32 v25, 0
	v_cvt_pk_bf16_f32 v20, v6, v7
	s_waitcnt lgkmcnt(0)
	v_add_f32_e32 v18, v18, v19
	ds_bpermute_b32 v19, v65, v18
	v_cvt_pk_bf16_f32 v21, v8, v9
	v_cvt_pk_fp8_f32 v25, v2, v3
	v_cvt_pk_fp8_f32 v24, v8, v9 op_sel:[0,0,1]
	v_mov_b32_e32 v8, 0
	s_waitcnt lgkmcnt(0)
	v_add_f32_e32 v18, v18, v19
	ds_bpermute_b32 v19, v66, v18
	v_mov_b32_e32 v9, 0
	v_cvt_pk_fp8_f32 v8, v14, v15
	v_cvt_pk_fp8_f32 v9, v10, v11
	v_cvt_pk_fp8_f32 v25, v4, v5 op_sel:[0,0,1]
	s_waitcnt lgkmcnt(0)
	v_add_f32_e32 v18, v18, v19
	ds_bpermute_b32 v19, v67, v18
	v_add_co_u32_e32 v6, vcc, s48, v58
	v_cvt_pk_fp8_f32 v8, v16, v17 op_sel:[0,0,1]
	v_cvt_pk_fp8_f32 v9, v12, v13 op_sel:[0,0,1]
	s_waitcnt lgkmcnt(0)
	v_add_f32_e32 v18, v18, v19
	ds_bpermute_b32 v19, v68, v18
	v_cvt_pk_bf16_f32 v22, v2, v3
	v_cvt_pk_bf16_f32 v23, v4, v5
	v_addc_co_u32_e32 v7, vcc, 0, v59, vcc
	s_waitcnt lgkmcnt(0)
	v_add_f32_e32 v18, v18, v19
	ds_bpermute_b32 v19, v69, v18
	global_store_dwordx4 v[6:7], v[20:23], off offset:2048 sc1
	global_store_dwordx2 v[60:61], v[24:25], off offset:3072 sc1
	v_cvt_pk_bf16_f32 v2, v14, v15
	v_cvt_pk_bf16_f32 v3, v16, v17
	v_cvt_pk_bf16_f32 v4, v10, v11
	v_cvt_pk_bf16_f32 v5, v12, v13
	global_store_dwordx4 v[6:7], v[2:5], off offset:3072 sc1
	global_store_dwordx2 v[60:61], v[8:9], off offset:3584 sc1
	s_and_saveexec_b64 s[36:37], s[6:7]
	s_cbranch_execz .LBB0_17
	s_waitcnt lgkmcnt(0)
	v_add_f32_e32 v2, v18, v19
	v_cndmask_b32_e64 v4, 0, v2, s[4:5]
	v_add_co_u32_e32 v2, vcc, 0x100000, v62
	s_nop 1
	v_addc_co_u32_e32 v3, vcc, 0, v63, vcc
	global_store_dword v[2:3], v4, off offset:192 sc1
	s_branch .LBB0_17

.LBB0_28:
	s_mul_hi_i32 s21, s20, 0x900000
	s_mul_i32 s20, s20, 0x900000
	s_add_u32 s20, s35, s20
	s_addc_u32 s21, s36, s21
	s_and_b32 s23, s24, 0x1e0
	s_add_i32 s16, s16, s23
	s_lshl_b32 s16, s16, 11
	s_waitcnt vmcnt(30)
	ds_write2_b32 v55, v22, v23 offset1:66
	s_waitcnt vmcnt(28)
	ds_write2_b32 v55, v24, v25 offset0:132 offset1:198
	s_waitcnt vmcnt(26)
	ds_write2_b32 v58, v26, v27 offset0:8 offset1:74
	s_waitcnt vmcnt(24)
	ds_write2_b32 v58, v28, v29 offset0:140 offset1:206
	s_waitcnt vmcnt(22)
	ds_write2_b32 v59, v30, v31 offset0:16 offset1:82
	s_waitcnt vmcnt(20)
	ds_write2_b32 v59, v32, v33 offset0:148 offset1:214
	s_waitcnt vmcnt(18)
	ds_write2_b32 v60, v34, v35 offset0:24 offset1:90
	s_waitcnt vmcnt(16)
	ds_write2_b32 v60, v36, v37 offset0:156 offset1:222
	s_waitcnt vmcnt(14)
	ds_write2_b32 v61, v38, v39 offset0:32 offset1:98
	s_waitcnt vmcnt(12)
	ds_write2_b32 v61, v40, v41 offset0:164 offset1:230
	s_waitcnt vmcnt(10)
	ds_write2_b32 v62, v42, v43 offset0:40 offset1:106
	s_waitcnt vmcnt(8)
	ds_write2_b32 v62, v44, v45 offset0:172 offset1:238
	s_waitcnt vmcnt(6)
	ds_write2_b32 v63, v46, v47 offset0:48 offset1:114
	s_waitcnt vmcnt(4)
	ds_write2_b32 v63, v48, v49 offset0:180 offset1:246
	s_waitcnt vmcnt(2)
	ds_write2_b32 v64, v52, v53 offset0:56 offset1:122
	s_waitcnt vmcnt(0)
	ds_write2_b32 v64, v50, v51 offset0:188 offset1:254
	s_add_u32 s16, s20, s16
	s_waitcnt lgkmcnt(0)
	s_addc_u32 s24, s21, 0
	s_ashr_i32 s23, s22, 31
	s_lshl_b64 s[20:21], s[22:23], 1
	ds_read2_b32 v[20:21], v56 offset1:33
	s_add_u32 s20, s16, s20
	s_waitcnt lgkmcnt(0)
	v_cvt_pk_bf16_f32 v20, v20, v21
	ds_read2_b32 v[22:23], v56 offset0:66 offset1:99
	s_addc_u32 s21, s24, s21
	v_mov_b32_e32 v11, v3
	s_waitcnt lgkmcnt(0)
	v_cvt_pk_bf16_f32 v21, v22, v23
	ds_read2_b32 v[22:23], v56 offset0:132 offset1:165
	v_lshl_add_u64 v[26:27], s[20:21], 0, v[10:11]
	v_mov_b32_e32 v13, v3
	s_waitcnt lgkmcnt(0)
	v_cvt_pk_bf16_f32 v22, v22, v23
	ds_read2_b32 v[24:25], v56 offset0:198 offset1:231
	s_waitcnt lgkmcnt(0)
	v_cvt_pk_bf16_f32 v23, v24, v25
	v_lshl_add_u64 v[28:29], v[26:27], 0, v[12:13]
	ds_read2_b32 v[24:25], v56 offset0:8 offset1:41
	global_store_dwordx4 v[28:29], v[20:23], off sc1
	v_mov_b32_e32 v15, v3
	v_lshl_add_u64 v[28:29], v[26:27], 0, v[14:15]
	s_waitcnt lgkmcnt(0)
	v_cvt_pk_bf16_f32 v20, v24, v25
	ds_read2_b32 v[22:23], v56 offset0:74 offset1:107
	s_waitcnt lgkmcnt(0)
	v_cvt_pk_bf16_f32 v21, v22, v23
	ds_read2_b32 v[22:23], v56 offset0:140 offset1:173
	s_waitcnt lgkmcnt(0)
	v_cvt_pk_bf16_f32 v22, v22, v23
	ds_read2_b32 v[24:25], v56 offset0:206 offset1:239
	s_waitcnt lgkmcnt(0)
	v_cvt_pk_bf16_f32 v23, v24, v25
	ds_read2_b32 v[24:25], v56 offset0:16 offset1:49
	global_store_dwordx4 v[28:29], v[20:23], off sc1
	v_mov_b32_e32 v17, v3
	v_lshl_add_u64 v[28:29], v[26:27], 0, v[16:17]
	s_waitcnt lgkmcnt(0)
	v_cvt_pk_bf16_f32 v20, v24, v25
	ds_read2_b32 v[22:23], v56 offset0:82 offset1:115
	s_waitcnt lgkmcnt(0)
	v_cvt_pk_bf16_f32 v21, v22, v23
	ds_read2_b32 v[22:23], v56 offset0:148 offset1:181
	s_waitcnt lgkmcnt(0)
	v_cvt_pk_bf16_f32 v22, v22, v23
	ds_read2_b32 v[24:25], v56 offset0:214 offset1:247
	s_waitcnt lgkmcnt(0)
	v_cvt_pk_bf16_f32 v23, v24, v25
	ds_read2_b32 v[24:25], v56 offset0:24 offset1:57
	global_store_dwordx4 v[28:29], v[20:23], off sc1
	v_mov_b32_e32 v19, v3
	s_waitcnt lgkmcnt(0)
	v_cvt_pk_bf16_f32 v20, v24, v25
	ds_read2_b32 v[22:23], v56 offset0:90 offset1:123
	s_waitcnt lgkmcnt(0)
	v_cvt_pk_bf16_f32 v21, v22, v23
	ds_read2_b32 v[22:23], v56 offset0:156 offset1:189
	s_waitcnt lgkmcnt(0)
	v_cvt_pk_bf16_f32 v22, v22, v23
	ds_read2_b32 v[24:25], v56 offset0:222 offset1:255
	s_waitcnt lgkmcnt(0)
	v_cvt_pk_bf16_f32 v23, v24, v25
	v_lshl_add_u64 v[24:25], v[26:27], 0, v[18:19]
	global_store_dwordx4 v[24:25], v[20:23], off sc1
	s_waitcnt lgkmcnt(0)

.LBB0_30:
	s_mul_hi_i32 s16, s93, 0x66666667
	s_lshr_b32 s20, s16, 31
	s_ashr_i32 s16, s16, 11
	s_add_i32 s20, s16, s20
	s_mul_i32 s16, s20, 0xffffec00
	s_add_i32 s24, s93, s16
	s_ashr_i32 s21, s20, 31
	s_mul_hi_i32 s25, s20, 0x300000
	s_mul_i32 s94, s20, 0x300000
	s_cmpk_gt_i32 s24, 0xeff
	s_mov_b64 s[22:23], -1
	s_cbranch_scc0 .LBB0_36
	s_cmpk_gt_u32 s24, 0x11ff
	s_cbranch_scc0 .LBB0_33
	s_lshl_b64 s[22:23], s[20:21], 21
	s_add_u32 s28, s44, s22
	s_mul_i32 s16, s20, 0xffffd800
	s_addc_u32 s29, s46, s23
	s_add_i32 s16, s54, s16
	s_and_b32 s16, s16, 0x7fffffc0
	s_addk_i32 s16, 0xdc00
	s_and_b32 s30, s52, 0x3e0
	s_lshl_b64 s[22:23], s[20:21], 22
	s_add_u32 s26, s12, s22
	s_addc_u32 s27, s13, s23
	s_lshl_b32 s22, s30, 11
	s_add_u32 s28, s28, s22
	s_addc_u32 s29, s29, 0
	s_lshl_b64 s[22:23], s[16:17], 1
	v_or_b32_e32 v20, s16, v54
	v_mov_b32_e32 v21, v3
	s_add_u32 s22, s28, s22
	v_lshlrev_b64 v[20:21], 12, v[20:21]
	s_addc_u32 s23, s29, s23
	v_lshl_add_u64 v[20:21], s[26:27], 0, v[20:21]
	s_lshl_b32 s16, s30, 2
	v_lshl_add_u64 v[20:21], v[20:21], 0, s[16:17]
	v_lshl_add_u64 v[20:21], v[20:21], 0, v[2:3]
	v_add_co_u32_e32 v22, vcc, s47, v20
	s_nop 1
	v_addc_co_u32_e32 v23, vcc, 0, v21, vcc
	v_add_co_u32_e32 v24, vcc, s48, v20
	s_nop 1
	v_addc_co_u32_e32 v25, vcc, 0, v21, vcc
	v_add_co_u32_e32 v26, vcc, s49, v20
	s_nop 1
	v_addc_co_u32_e32 v27, vcc, 0, v21, vcc
	v_add_co_u32_e32 v28, vcc, s56, v20
	s_nop 1
	v_addc_co_u32_e32 v29, vcc, 0, v21, vcc
	v_add_co_u32_e32 v30, vcc, s57, v20
	s_nop 1
	v_addc_co_u32_e32 v31, vcc, 0, v21, vcc
	v_add_co_u32_e32 v32, vcc, s58, v20
	s_nop 1
	v_addc_co_u32_e32 v33, vcc, 0, v21, vcc
	v_add_co_u32_e32 v34, vcc, s59, v20
	s_nop 1
	v_addc_co_u32_e32 v35, vcc, 0, v21, vcc
	global_load_dword v9, v[20:21], off nt
	global_load_dword v11, v[22:23], off nt
	global_load_dword v13, v[24:25], off nt
	global_load_dword v15, v[26:27], off nt
	global_load_dword v17, v[28:29], off nt
	global_load_dword v19, v[30:31], off nt
	global_load_dword v38, v[32:33], off nt
	global_load_dword v39, v[34:35], off nt
	v_add_co_u32_e32 v22, vcc, s60, v20
	s_nop 1
	v_addc_co_u32_e32 v23, vcc, 0, v21, vcc
	v_add_co_u32_e32 v24, vcc, s61, v20
	s_nop 1
	v_addc_co_u32_e32 v25, vcc, 0, v21, vcc
	v_add_co_u32_e32 v26, vcc, s62, v20
	s_nop 1
	v_addc_co_u32_e32 v27, vcc, 0, v21, vcc
	v_add_co_u32_e32 v28, vcc, s63, v20
	s_nop 1
	v_addc_co_u32_e32 v29, vcc, 0, v21, vcc
	v_add_co_u32_e32 v30, vcc, s64, v20
	s_nop 1
	v_addc_co_u32_e32 v31, vcc, 0, v21, vcc
	v_add_co_u32_e32 v32, vcc, s65, v20
	s_nop 1
	v_addc_co_u32_e32 v33, vcc, 0, v21, vcc
	v_add_co_u32_e32 v34, vcc, s66, v20
	s_nop 1
	v_addc_co_u32_e32 v35, vcc, 0, v21, vcc
	v_add_co_u32_e32 v36, vcc, s67, v20
	s_nop 1
	v_addc_co_u32_e32 v37, vcc, 0, v21, vcc
	global_load_dword v40, v[22:23], off nt
	global_load_dword v41, v[24:25], off nt
	global_load_dword v42, v[26:27], off nt
	global_load_dword v43, v[28:29], off nt
	global_load_dword v44, v[30:31], off nt
	global_load_dword v45, v[32:33], off nt
	global_load_dword v46, v[34:35], off nt
	global_load_dword v47, v[36:37], off nt
	v_add_co_u32_e32 v22, vcc, s68, v20
	s_nop 1
	v_addc_co_u32_e32 v23, vcc, 0, v21, vcc
	v_add_co_u32_e32 v24, vcc, s69, v20
	s_nop 1
	v_addc_co_u32_e32 v25, vcc, 0, v21, vcc
	v_add_co_u32_e32 v26, vcc, s70, v20
	s_nop 1
	v_addc_co_u32_e32 v27, vcc, 0, v21, vcc
	v_add_co_u32_e32 v28, vcc, s71, v20
	s_nop 1
	v_addc_co_u32_e32 v29, vcc, 0, v21, vcc
	v_add_co_u32_e32 v30, vcc, s72, v20
	s_nop 1
	v_addc_co_u32_e32 v31, vcc, 0, v21, vcc
	v_add_co_u32_e32 v32, vcc, s73, v20
	s_nop 1
	v_addc_co_u32_e32 v33, vcc, 0, v21, vcc
	v_add_co_u32_e32 v34, vcc, s74, v20
	s_nop 1
	v_addc_co_u32_e32 v35, vcc, 0, v21, vcc
	v_add_co_u32_e32 v36, vcc, s75, v20
	s_nop 1
	v_addc_co_u32_e32 v37, vcc, 0, v21, vcc
	global_load_dword v48, v[22:23], off nt
	global_load_dword v49, v[24:25], off nt
	global_load_dword v50, v[26:27], off nt
	global_load_dword v51, v[28:29], off nt
	global_load_dword v52, v[30:31], off nt
	global_load_dword v53, v[32:33], off nt
	global_load_dword v65, v[34:35], off nt
	s_nop 0
	global_load_dword v36, v[36:37], off nt
	v_add_co_u32_e32 v22, vcc, s76, v20
	s_nop 1
	v_addc_co_u32_e32 v23, vcc, 0, v21, vcc
	v_add_co_u32_e32 v24, vcc, s77, v20
	s_nop 1
	v_addc_co_u32_e32 v25, vcc, 0, v21, vcc
	v_add_co_u32_e32 v26, vcc, s78, v20
	s_nop 1
	v_addc_co_u32_e32 v27, vcc, 0, v21, vcc
	v_add_co_u32_e32 v28, vcc, s79, v20
	s_nop 1
	v_addc_co_u32_e32 v29, vcc, 0, v21, vcc
	v_add_co_u32_e32 v30, vcc, s80, v20
	s_nop 1
	v_addc_co_u32_e32 v31, vcc, 0, v21, vcc
	v_add_co_u32_e32 v32, vcc, s81, v20
	s_nop 1
	v_addc_co_u32_e32 v33, vcc, 0, v21, vcc
	v_add_co_u32_e32 v34, vcc, s82, v20
	s_nop 1
	v_addc_co_u32_e32 v35, vcc, 0, v21, vcc
	v_add_co_u32_e32 v20, vcc, s83, v20
	s_nop 1
	v_addc_co_u32_e32 v21, vcc, 0, v21, vcc
	global_load_dword v22, v[22:23], off nt
	s_nop 0
	global_load_dword v23, v[24:25], off nt
	s_nop 0
	global_load_dword v24, v[26:27], off nt
	global_load_dword v25, v[28:29], off nt
	s_nop 0
	global_load_dword v26, v[30:31], off nt
	global_load_dword v27, v[32:33], off nt
	global_load_dword v28, v[34:35], off nt
	s_nop 0
	global_load_dword v20, v[20:21], off nt
	s_waitcnt vmcnt(30)
	ds_write2_b32 v55, v9, v11 offset1:66
	s_waitcnt vmcnt(28)
	ds_write2_b32 v55, v13, v15 offset0:132 offset1:198
	s_waitcnt vmcnt(26)
	ds_write2_b32 v58, v17, v19 offset0:8 offset1:74
	s_waitcnt vmcnt(24)
	ds_write2_b32 v58, v38, v39 offset0:140 offset1:206
	s_waitcnt vmcnt(22)
	ds_write2_b32 v59, v40, v41 offset0:16 offset1:82
	s_waitcnt vmcnt(20)
	ds_write2_b32 v59, v42, v43 offset0:148 offset1:214
	s_waitcnt vmcnt(18)
	ds_write2_b32 v60, v44, v45 offset0:24 offset1:90
	s_waitcnt vmcnt(16)
	ds_write2_b32 v60, v46, v47 offset0:156 offset1:222
	s_waitcnt vmcnt(14)
	ds_write2_b32 v61, v48, v49 offset0:32 offset1:98
	s_waitcnt vmcnt(12)
	ds_write2_b32 v61, v50, v51 offset0:164 offset1:230
	s_waitcnt vmcnt(10)
	ds_write2_b32 v62, v52, v53 offset0:40 offset1:106
	s_waitcnt vmcnt(8)
	ds_write2_b32 v62, v65, v36 offset0:172 offset1:238
	s_waitcnt vmcnt(6)
	ds_write2_b32 v63, v22, v23 offset0:48 offset1:114
	s_waitcnt vmcnt(4)
	ds_write2_b32 v63, v24, v25 offset0:180 offset1:246
	s_waitcnt vmcnt(2)
	ds_write2_b32 v64, v26, v27 offset0:56 offset1:122
	s_waitcnt vmcnt(0)
	ds_write2_b32 v64, v28, v20 offset0:188 offset1:254
	s_waitcnt lgkmcnt(0)
	ds_read2_b32 v[20:21], v56 offset1:33
	s_waitcnt lgkmcnt(0)
	v_cvt_pk_bf16_f32 v20, v20, v21
	ds_read2_b32 v[22:23], v56 offset0:66 offset1:99
	v_mov_b32_e32 v11, v3
	s_waitcnt lgkmcnt(0)
	v_cvt_pk_bf16_f32 v21, v22, v23
	ds_read2_b32 v[22:23], v56 offset0:132 offset1:165
	v_lshl_add_u64 v[26:27], s[22:23], 0, v[10:11]
	v_mov_b32_e32 v13, v3
	s_waitcnt lgkmcnt(0)
	v_cvt_pk_bf16_f32 v22, v22, v23
	ds_read2_b32 v[24:25], v56 offset0:198 offset1:231
	s_waitcnt lgkmcnt(0)
	v_cvt_pk_bf16_f32 v23, v24, v25
	v_lshl_add_u64 v[28:29], v[26:27], 0, v[12:13]
	ds_read2_b32 v[24:25], v56 offset0:8 offset1:41
	global_store_dwordx4 v[28:29], v[20:23], off sc1
	v_mov_b32_e32 v15, v3
	v_lshl_add_u64 v[28:29], v[26:27], 0, v[14:15]
	s_waitcnt lgkmcnt(0)
	v_cvt_pk_bf16_f32 v20, v24, v25
	ds_read2_b32 v[22:23], v56 offset0:74 offset1:107
	s_waitcnt lgkmcnt(0)
	v_cvt_pk_bf16_f32 v21, v22, v23
	ds_read2_b32 v[22:23], v56 offset0:140 offset1:173
	s_waitcnt lgkmcnt(0)
	v_cvt_pk_bf16_f32 v22, v22, v23
	ds_read2_b32 v[24:25], v56 offset0:206 offset1:239
	s_waitcnt lgkmcnt(0)
	v_cvt_pk_bf16_f32 v23, v24, v25
	ds_read2_b32 v[24:25], v56 offset0:16 offset1:49
	global_store_dwordx4 v[28:29], v[20:23], off sc1
	v_mov_b32_e32 v17, v3
	v_lshl_add_u64 v[28:29], v[26:27], 0, v[16:17]
	s_waitcnt lgkmcnt(0)
	v_cvt_pk_bf16_f32 v20, v24, v25
	ds_read2_b32 v[22:23], v56 offset0:82 offset1:115
	s_waitcnt lgkmcnt(0)
	v_cvt_pk_bf16_f32 v21, v22, v23
	ds_read2_b32 v[22:23], v56 offset0:148 offset1:181
	s_waitcnt lgkmcnt(0)
	v_cvt_pk_bf16_f32 v22, v22, v23
	ds_read2_b32 v[24:25], v56 offset0:214 offset1:247
	s_waitcnt lgkmcnt(0)
	v_cvt_pk_bf16_f32 v23, v24, v25
	ds_read2_b32 v[24:25], v56 offset0:24 offset1:57
	global_store_dwordx4 v[28:29], v[20:23], off sc1
	v_mov_b32_e32 v19, v3
	s_mov_b64 s[22:23], 0
	s_waitcnt lgkmcnt(0)
	v_cvt_pk_bf16_f32 v20, v24, v25
	ds_read2_b32 v[22:23], v56 offset0:90 offset1:123
	s_waitcnt lgkmcnt(0)
	v_cvt_pk_bf16_f32 v21, v22, v23
	ds_read2_b32 v[22:23], v56 offset0:156 offset1:189
	s_waitcnt lgkmcnt(0)
	v_cvt_pk_bf16_f32 v22, v22, v23
	ds_read2_b32 v[24:25], v56 offset0:222 offset1:255
	s_waitcnt lgkmcnt(0)
	v_cvt_pk_bf16_f32 v23, v24, v25
	v_lshl_add_u64 v[24:25], v[26:27], 0, v[18:19]
	global_store_dwordx4 v[24:25], v[20:23], off sc1
	s_waitcnt lgkmcnt(0)
.LBB0_33:
	s_andn2_b64 vcc, exec, s[22:23]
	s_cbranch_vccnz .LBB0_35
	s_add_u32 s16, s37, s94
	s_addc_u32 s28, s43, s25
	s_add_i32 s22, s24, 0xfffff100
	s_lshr_b32 s29, s22, 8
	s_lshl_b32 s22, s29, 3
	s_load_dwordx2 s[22:23], s[0:1], s22 offset:0x58
	s_and_b32 s30, s54, 0x1c0
	s_and_b32 s31, s52, 0x3e0
	s_lshl_b64 s[26:27], s[20:21], 21
	s_mul_i32 s21, s31, 0xc00
	s_waitcnt lgkmcnt(0)
	s_add_u32 s26, s22, s26
	s_addc_u32 s27, s23, s27
	s_add_u32 s16, s16, s21
	s_addc_u32 s21, s28, 0
	s_lshl_b32 s22, s29, 10
	s_add_u32 s16, s16, s22
	s_addc_u32 s21, s21, 0
	s_lshl_b32 s22, s30, 1
	v_or_b32_e32 v9, s30, v54
	s_add_u32 s22, s16, s22
	v_lshlrev_b32_e32 v20, 12, v9
	v_mov_b32_e32 v21, v3
	s_addc_u32 s23, s21, 0
	v_lshl_add_u64 v[20:21], s[26:27], 0, v[20:21]
	s_lshl_b32 s16, s31, 2
	v_lshl_add_u64 v[20:21], v[20:21], 0, s[16:17]
	v_lshl_add_u64 v[20:21], v[20:21], 0, v[2:3]
	v_add_co_u32_e32 v22, vcc, s47, v20
	s_nop 1
	v_addc_co_u32_e32 v23, vcc, 0, v21, vcc
	v_add_co_u32_e32 v24, vcc, s48, v20
	s_nop 1
	v_addc_co_u32_e32 v25, vcc, 0, v21, vcc
	v_add_co_u32_e32 v26, vcc, s49, v20
	s_nop 1
	v_addc_co_u32_e32 v27, vcc, 0, v21, vcc
	v_add_co_u32_e32 v28, vcc, s56, v20
	s_nop 1
	v_addc_co_u32_e32 v29, vcc, 0, v21, vcc
	v_add_co_u32_e32 v30, vcc, s57, v20
	s_nop 1
	v_addc_co_u32_e32 v31, vcc, 0, v21, vcc
	v_add_co_u32_e32 v32, vcc, s58, v20
	s_nop 1
	v_addc_co_u32_e32 v33, vcc, 0, v21, vcc
	v_add_co_u32_e32 v34, vcc, s59, v20
	s_nop 1
	v_addc_co_u32_e32 v35, vcc, 0, v21, vcc
	global_load_dword v9, v[20:21], off nt
	global_load_dword v11, v[22:23], off nt
	global_load_dword v13, v[24:25], off nt
	global_load_dword v15, v[26:27], off nt
	global_load_dword v17, v[28:29], off nt
	global_load_dword v19, v[30:31], off nt
	global_load_dword v38, v[32:33], off nt
	global_load_dword v39, v[34:35], off nt
	v_add_co_u32_e32 v22, vcc, s60, v20
	s_nop 1
	v_addc_co_u32_e32 v23, vcc, 0, v21, vcc
	v_add_co_u32_e32 v24, vcc, s61, v20
	s_nop 1
	v_addc_co_u32_e32 v25, vcc, 0, v21, vcc
	v_add_co_u32_e32 v26, vcc, s62, v20
	s_nop 1
	v_addc_co_u32_e32 v27, vcc, 0, v21, vcc
	v_add_co_u32_e32 v28, vcc, s63, v20
	s_nop 1
	v_addc_co_u32_e32 v29, vcc, 0, v21, vcc
	v_add_co_u32_e32 v30, vcc, s64, v20
	s_nop 1
	v_addc_co_u32_e32 v31, vcc, 0, v21, vcc
	v_add_co_u32_e32 v32, vcc, s65, v20
	s_nop 1
	v_addc_co_u32_e32 v33, vcc, 0, v21, vcc
	v_add_co_u32_e32 v34, vcc, s66, v20
	s_nop 1
	v_addc_co_u32_e32 v35, vcc, 0, v21, vcc
	v_add_co_u32_e32 v36, vcc, s67, v20
	s_nop 1
	v_addc_co_u32_e32 v37, vcc, 0, v21, vcc
	global_load_dword v40, v[22:23], off nt
	global_load_dword v41, v[24:25], off nt
	global_load_dword v42, v[26:27], off nt
	global_load_dword v43, v[28:29], off nt
	global_load_dword v44, v[30:31], off nt
	global_load_dword v45, v[32:33], off nt
	global_load_dword v46, v[34:35], off nt
	global_load_dword v47, v[36:37], off nt
	v_add_co_u32_e32 v22, vcc, s68, v20
	s_nop 1
	v_addc_co_u32_e32 v23, vcc, 0, v21, vcc
	v_add_co_u32_e32 v24, vcc, s69, v20
	s_nop 1
	v_addc_co_u32_e32 v25, vcc, 0, v21, vcc
	v_add_co_u32_e32 v26, vcc, s70, v20
	s_nop 1
	v_addc_co_u32_e32 v27, vcc, 0, v21, vcc
	v_add_co_u32_e32 v28, vcc, s71, v20
	s_nop 1
	v_addc_co_u32_e32 v29, vcc, 0, v21, vcc
	v_add_co_u32_e32 v30, vcc, s72, v20
	s_nop 1
	v_addc_co_u32_e32 v31, vcc, 0, v21, vcc
	v_add_co_u32_e32 v32, vcc, s73, v20
	s_nop 1
	v_addc_co_u32_e32 v33, vcc, 0, v21, vcc
	v_add_co_u32_e32 v34, vcc, s74, v20
	s_nop 1
	v_addc_co_u32_e32 v35, vcc, 0, v21, vcc
	v_add_co_u32_e32 v36, vcc, s75, v20
	s_nop 1
	v_addc_co_u32_e32 v37, vcc, 0, v21, vcc
	global_load_dword v48, v[22:23], off nt
	global_load_dword v49, v[24:25], off nt
	global_load_dword v50, v[26:27], off nt
	global_load_dword v51, v[28:29], off nt
	global_load_dword v52, v[30:31], off nt
	global_load_dword v53, v[32:33], off nt
	global_load_dword v65, v[34:35], off nt
	s_nop 0
	global_load_dword v36, v[36:37], off nt
	v_add_co_u32_e32 v22, vcc, s76, v20
	s_nop 1
	v_addc_co_u32_e32 v23, vcc, 0, v21, vcc
	v_add_co_u32_e32 v24, vcc, s77, v20
	s_nop 1
	v_addc_co_u32_e32 v25, vcc, 0, v21, vcc
	v_add_co_u32_e32 v26, vcc, s78, v20
	s_nop 1
	v_addc_co_u32_e32 v27, vcc, 0, v21, vcc
	v_add_co_u32_e32 v28, vcc, s79, v20
	s_nop 1
	v_addc_co_u32_e32 v29, vcc, 0, v21, vcc
	v_add_co_u32_e32 v30, vcc, s80, v20
	s_nop 1
	v_addc_co_u32_e32 v31, vcc, 0, v21, vcc
	v_add_co_u32_e32 v32, vcc, s81, v20
	s_nop 1
	v_addc_co_u32_e32 v33, vcc, 0, v21, vcc
	v_add_co_u32_e32 v34, vcc, s82, v20
	s_nop 1
	v_addc_co_u32_e32 v35, vcc, 0, v21, vcc
	v_add_co_u32_e32 v20, vcc, s83, v20
	s_nop 1
	v_addc_co_u32_e32 v21, vcc, 0, v21, vcc
	global_load_dword v22, v[22:23], off nt
	s_nop 0
	global_load_dword v23, v[24:25], off nt
	s_nop 0
	global_load_dword v24, v[26:27], off nt
	global_load_dword v25, v[28:29], off nt
	s_nop 0
	global_load_dword v26, v[30:31], off nt
	global_load_dword v27, v[32:33], off nt
	global_load_dword v28, v[34:35], off nt
	s_nop 0
	global_load_dword v20, v[20:21], off nt
	s_waitcnt vmcnt(30)
	ds_write2_b32 v55, v9, v11 offset1:66
	s_waitcnt vmcnt(28)
	ds_write2_b32 v55, v13, v15 offset0:132 offset1:198
	s_waitcnt vmcnt(26)
	ds_write2_b32 v58, v17, v19 offset0:8 offset1:74
	s_waitcnt vmcnt(24)
	ds_write2_b32 v58, v38, v39 offset0:140 offset1:206
	s_waitcnt vmcnt(22)
	ds_write2_b32 v59, v40, v41 offset0:16 offset1:82
	s_waitcnt vmcnt(20)
	ds_write2_b32 v59, v42, v43 offset0:148 offset1:214
	s_waitcnt vmcnt(18)
	ds_write2_b32 v60, v44, v45 offset0:24 offset1:90
	s_waitcnt vmcnt(16)
	ds_write2_b32 v60, v46, v47 offset0:156 offset1:222
	s_waitcnt vmcnt(14)
	ds_write2_b32 v61, v48, v49 offset0:32 offset1:98
	s_waitcnt vmcnt(12)
	ds_write2_b32 v61, v50, v51 offset0:164 offset1:230
	s_waitcnt vmcnt(10)
	ds_write2_b32 v62, v52, v53 offset0:40 offset1:106
	s_waitcnt vmcnt(8)
	ds_write2_b32 v62, v65, v36 offset0:172 offset1:238
	s_waitcnt vmcnt(6)
	ds_write2_b32 v63, v22, v23 offset0:48 offset1:114
	s_waitcnt vmcnt(4)
	ds_write2_b32 v63, v24, v25 offset0:180 offset1:246
	s_waitcnt vmcnt(2)
	ds_write2_b32 v64, v26, v27 offset0:56 offset1:122
	s_waitcnt vmcnt(0)
	ds_write2_b32 v64, v28, v20 offset0:188 offset1:254
	s_waitcnt lgkmcnt(0)
	ds_read2_b32 v[20:21], v56 offset1:33
	s_waitcnt lgkmcnt(0)
	v_cvt_pk_bf16_f32 v20, v20, v21
	ds_read2_b32 v[22:23], v56 offset0:66 offset1:99
	v_mov_b32_e32 v11, v3
	s_waitcnt lgkmcnt(0)
	v_cvt_pk_bf16_f32 v21, v22, v23
	ds_read2_b32 v[22:23], v56 offset0:132 offset1:165
	v_lshl_add_u64 v[26:27], s[22:23], 0, v[10:11]
	v_mov_b32_e32 v9, v3
	s_waitcnt lgkmcnt(0)
	v_cvt_pk_bf16_f32 v22, v22, v23
	ds_read2_b32 v[24:25], v56 offset0:198 offset1:231
	s_waitcnt lgkmcnt(0)
	v_cvt_pk_bf16_f32 v23, v24, v25
	v_lshl_add_u64 v[26:27], v[26:27], 0, v[8:9]
	ds_read2_b32 v[24:25], v56 offset0:8 offset1:41
	global_store_dwordx4 v[26:27], v[20:23], off sc1
	v_add_co_u32_e32 v28, vcc, s49, v26
	s_waitcnt lgkmcnt(0)
	v_cvt_pk_bf16_f32 v20, v24, v25
	ds_read2_b32 v[22:23], v56 offset0:74 offset1:107
	s_waitcnt lgkmcnt(0)
	v_cvt_pk_bf16_f32 v21, v22, v23
	ds_read2_b32 v[22:23], v56 offset0:140 offset1:173
	s_waitcnt lgkmcnt(0)
	v_cvt_pk_bf16_f32 v22, v22, v23
	ds_read2_b32 v[24:25], v56 offset0:206 offset1:239
	s_waitcnt lgkmcnt(0)
	v_cvt_pk_bf16_f32 v23, v24, v25
	v_addc_co_u32_e32 v29, vcc, 0, v27, vcc
	ds_read2_b32 v[24:25], v56 offset0:16 offset1:49
	global_store_dwordx4 v[28:29], v[20:23], off sc1
	v_add_co_u32_e32 v28, vcc, s58, v26
	s_waitcnt lgkmcnt(0)
	v_cvt_pk_bf16_f32 v20, v24, v25
	ds_read2_b32 v[22:23], v56 offset0:82 offset1:115
	s_waitcnt lgkmcnt(0)
	v_cvt_pk_bf16_f32 v21, v22, v23
	ds_read2_b32 v[22:23], v56 offset0:148 offset1:181
	s_waitcnt lgkmcnt(0)
	v_cvt_pk_bf16_f32 v22, v22, v23
	ds_read2_b32 v[24:25], v56 offset0:214 offset1:247
	s_waitcnt lgkmcnt(0)
	v_cvt_pk_bf16_f32 v23, v24, v25
	v_addc_co_u32_e32 v29, vcc, 0, v27, vcc
	ds_read2_b32 v[24:25], v56 offset0:24 offset1:57
	global_store_dwordx4 v[28:29], v[20:23], off sc1
	s_waitcnt lgkmcnt(0)
	s_nop 0
	v_cvt_pk_bf16_f32 v20, v24, v25
	ds_read2_b32 v[22:23], v56 offset0:90 offset1:123
	s_waitcnt lgkmcnt(0)
	v_cvt_pk_bf16_f32 v21, v22, v23
	ds_read2_b32 v[22:23], v56 offset0:156 offset1:189
	s_waitcnt lgkmcnt(0)
	v_cvt_pk_bf16_f32 v22, v22, v23
	ds_read2_b32 v[24:25], v56 offset0:222 offset1:255
	s_waitcnt lgkmcnt(0)
	v_cvt_pk_bf16_f32 v23, v24, v25
	v_add_co_u32_e32 v24, vcc, 0x12000, v26
	s_nop 1
	v_addc_co_u32_e32 v25, vcc, 0, v27, vcc
	global_store_dwordx4 v[24:25], v[20:23], off sc1
	s_waitcnt lgkmcnt(0)

.LBB0_36:
	s_andn2_b64 vcc, exec, s[22:23]
	s_cbranch_vccnz .LBB0_29
	s_mul_i32 s16, s24, 0xffff8889
	s_lshr_b32 s16, s16, 16
	s_add_i32 s16, s16, s24
	s_sext_i32_i16 s21, s16
	s_ashr_i32 s21, s21, 7
	s_bfe_u32 s16, s16, 0x1000f
	s_add_i32 s16, s21, s16
	s_sext_i32_i16 s22, s16
	s_mulk_i32 s16, 0xf0
	s_sub_i32 s16, s24, s16
	s_sext_i32_i16 s21, s16
	s_lshl_b32 s22, s22, 6
	s_lshl_b32 s24, s21, 5
	s_mul_i32 s23, s20, 0x1e00000
	s_mul_hi_i32 s16, s20, 0x1e00000
	s_add_u32 s28, s6, s23
	s_addc_u32 s29, s7, s16
	s_lshl_b32 s26, s20, 10
	s_ashr_i32 s27, s26, 31
	s_lshl_b64 s[26:27], s[26:27], 2
	s_add_u32 s26, s4, s26
	s_addc_u32 s27, s5, s27
	v_or_b32_e32 v20, s22, v54
	s_mov_b64 s[30:31], -1
	s_cmpk_gt_i32 s21, 0x8f
	v_mul_hi_i32_i24_e32 v23, 0x7800, v20
	v_mul_i32_i24_e32 v22, 0x7800, v20
	s_cbranch_scc0 .LBB0_39
	s_add_u32 s16, s50, s94
	s_addc_u32 s23, s51, s25
	s_ashr_i32 s25, s24, 31
	s_lshl_b64 s[30:31], s[24:25], 10
	v_lshl_add_u64 v[24:25], s[28:29], 0, v[22:23]
	s_mov_b32 s25, s17
	v_lshl_add_u64 v[24:25], s[24:25], 2, v[24:25]
	v_lshl_add_u64 v[24:25], v[24:25], 0, v[2:3]
	s_mov_b32 s25, 0xf000
	v_add_co_u32_e32 v26, vcc, s25, v24
	s_mov_b32 s25, 0x2d000
	s_nop 0
	v_addc_co_u32_e32 v27, vcc, 0, v25, vcc
	v_add_co_u32_e32 v28, vcc, s67, v24
	v_ashrrev_i32_e32 v21, 31, v20
	s_nop 0
	v_addc_co_u32_e32 v29, vcc, 0, v25, vcc
	v_add_co_u32_e32 v30, vcc, s25, v24
	s_mov_b32 s25, 0x4b000
	s_nop 0
	v_addc_co_u32_e32 v31, vcc, 0, v25, vcc
	v_add_co_u32_e32 v32, vcc, s82, v24
	s_add_u32 s16, s16, s30
	s_nop 0
	v_addc_co_u32_e32 v33, vcc, 0, v25, vcc
	v_add_co_u32_e32 v34, vcc, s25, v24
	s_mov_b32 s25, 0x5a000
	s_nop 0
	v_addc_co_u32_e32 v35, vcc, 0, v25, vcc
	v_add_co_u32_e32 v36, vcc, s25, v24
	s_mov_b32 s25, 0x69000
	s_nop 0
	v_addc_co_u32_e32 v37, vcc, 0, v25, vcc
	v_add_co_u32_e32 v38, vcc, s25, v24
	s_mov_b32 s25, 0x78000
	s_nop 0
	v_addc_co_u32_e32 v39, vcc, 0, v25, vcc
	global_load_dword v9, v[24:25], off nt
	global_load_dword v11, v[26:27], off nt
	global_load_dword v13, v[28:29], off nt
	global_load_dword v15, v[30:31], off nt
	global_load_dword v17, v[32:33], off nt
	global_load_dword v19, v[34:35], off nt
	global_load_dword v42, v[36:37], off nt
	global_load_dword v43, v[38:39], off nt
	v_add_co_u32_e32 v26, vcc, s25, v24
	s_mov_b32 s25, 0x87000
	s_nop 0
	v_addc_co_u32_e32 v27, vcc, 0, v25, vcc
	v_add_co_u32_e32 v28, vcc, s25, v24
	s_mov_b32 s25, 0x96000
	s_nop 0
	v_addc_co_u32_e32 v29, vcc, 0, v25, vcc
	v_add_co_u32_e32 v30, vcc, s25, v24
	s_mov_b32 s25, 0xa5000
	s_nop 0
	v_addc_co_u32_e32 v31, vcc, 0, v25, vcc
	v_add_co_u32_e32 v32, vcc, s25, v24
	s_mov_b32 s25, 0xb4000
	s_nop 0
	v_addc_co_u32_e32 v33, vcc, 0, v25, vcc
	v_add_co_u32_e32 v34, vcc, s25, v24
	s_mov_b32 s25, 0xc3000
	s_nop 0
	v_addc_co_u32_e32 v35, vcc, 0, v25, vcc
	v_add_co_u32_e32 v36, vcc, s25, v24
	s_mov_b32 s25, 0xd2000
	s_nop 0
	v_addc_co_u32_e32 v37, vcc, 0, v25, vcc
	v_add_co_u32_e32 v38, vcc, s25, v24
	s_mov_b32 s25, 0xe1000
	s_nop 0
	v_addc_co_u32_e32 v39, vcc, 0, v25, vcc
	v_add_co_u32_e32 v40, vcc, s25, v24
	s_mov_b32 s25, 0xf0000
	s_nop 0
	v_addc_co_u32_e32 v41, vcc, 0, v25, vcc
	global_load_dword v44, v[26:27], off nt
	global_load_dword v45, v[28:29], off nt
	global_load_dword v46, v[30:31], off nt
	global_load_dword v47, v[32:33], off nt
	global_load_dword v48, v[34:35], off nt
	global_load_dword v49, v[36:37], off nt
	global_load_dword v50, v[38:39], off nt
	global_load_dword v51, v[40:41], off nt
	v_add_co_u32_e32 v26, vcc, s25, v24
	s_mov_b32 s25, 0xff000
	s_nop 0
	v_addc_co_u32_e32 v27, vcc, 0, v25, vcc
	v_add_co_u32_e32 v28, vcc, s25, v24
	s_mov_b32 s25, 0x10e000
	s_nop 0
	v_addc_co_u32_e32 v29, vcc, 0, v25, vcc
	v_add_co_u32_e32 v30, vcc, s25, v24
	s_mov_b32 s25, 0x11d000
	s_nop 0
	v_addc_co_u32_e32 v31, vcc, 0, v25, vcc
	v_add_co_u32_e32 v32, vcc, s25, v24
	s_mov_b32 s25, 0x12c000
	s_nop 0
	v_addc_co_u32_e32 v33, vcc, 0, v25, vcc
	v_add_co_u32_e32 v34, vcc, s25, v24
	s_mov_b32 s25, 0x13b000
	s_nop 0
	v_addc_co_u32_e32 v35, vcc, 0, v25, vcc
	v_add_co_u32_e32 v36, vcc, s25, v24
	s_mov_b32 s25, 0x14a000
	s_nop 0
	v_addc_co_u32_e32 v37, vcc, 0, v25, vcc
	v_add_co_u32_e32 v38, vcc, s25, v24
	s_mov_b32 s25, 0x159000
	s_nop 0
	v_addc_co_u32_e32 v39, vcc, 0, v25, vcc
	v_add_co_u32_e32 v40, vcc, s25, v24
	s_addc_u32 s23, s23, s31
	s_nop 0
	v_addc_co_u32_e32 v41, vcc, 0, v25, vcc
	global_load_dword v52, v[26:27], off nt
	global_load_dword v53, v[28:29], off nt
	global_load_dword v65, v[30:31], off nt
	global_load_dword v66, v[32:33], off nt
	global_load_dword v67, v[34:35], off nt
	global_load_dword v68, v[36:37], off nt
	global_load_dword v69, v[38:39], off nt
	global_load_dword v70, v[40:41], off nt
	v_add_co_u32_e32 v26, vcc, s84, v24
	v_lshl_add_u64 v[30:31], v[20:21], 2, s[26:27]
	s_nop 0
	v_addc_co_u32_e32 v27, vcc, 0, v25, vcc
	v_add_co_u32_e32 v28, vcc, s85, v24
	global_load_dword v21, v[30:31], off
	global_load_dword v71, v[30:31], off offset:8
	global_load_dword v72, v[30:31], off offset:16
	global_load_dword v73, v[30:31], off offset:24
	v_addc_co_u32_e32 v29, vcc, 0, v25, vcc
	v_add_co_u32_e32 v32, vcc, s86, v24
	global_load_dword v74, v[30:31], off offset:32
	global_load_dword v75, v[30:31], off offset:40
	global_load_dword v76, v[30:31], off offset:48
	global_load_dword v77, v[30:31], off offset:56
	v_addc_co_u32_e32 v33, vcc, 0, v25, vcc
	v_add_co_u32_e32 v34, vcc, s87, v24
	global_load_dword v78, v[30:31], off offset:64
	global_load_dword v79, v[30:31], off offset:72
	global_load_dword v80, v[30:31], off offset:80
	global_load_dword v81, v[30:31], off offset:88
	v_addc_co_u32_e32 v35, vcc, 0, v25, vcc
	v_add_co_u32_e32 v36, vcc, s88, v24
	global_load_dword v82, v[30:31], off offset:96
	global_load_dword v83, v[30:31], off offset:104
	global_load_dword v84, v[30:31], off offset:112
	global_load_dword v85, v[30:31], off offset:120
	v_addc_co_u32_e32 v37, vcc, 0, v25, vcc
	v_add_co_u32_e32 v38, vcc, s89, v24
	global_load_dword v86, v[30:31], off offset:128
	global_load_dword v87, v[30:31], off offset:136
	global_load_dword v88, v[30:31], off offset:144
	global_load_dword v89, v[30:31], off offset:152
	v_addc_co_u32_e32 v39, vcc, 0, v25, vcc
	v_add_co_u32_e32 v40, vcc, s90, v24
	s_ashr_i32 s25, s22, 31
	s_nop 0
	v_addc_co_u32_e32 v41, vcc, 0, v25, vcc
	global_load_dword v90, v[30:31], off offset:160
	global_load_dword v91, v[30:31], off offset:168
	global_load_dword v92, v[30:31], off offset:176
	global_load_dword v93, v[30:31], off offset:184
	global_load_dword v94, v[30:31], off offset:192
	global_load_dword v95, v[30:31], off offset:200
	global_load_dword v96, v[30:31], off offset:208
	s_nop 0
	global_load_dword v26, v[26:27], off nt
	s_nop 0
	global_load_dword v27, v[28:29], off nt
	s_nop 0
	global_load_dword v28, v[32:33], off nt
	global_load_dword v29, v[34:35], off nt
	s_nop 0
	global_load_dword v32, v[36:37], off nt
	global_load_dword v33, v[38:39], off nt
	global_load_dword v34, v[40:41], off nt
	global_load_dword v35, v[30:31], off offset:216
	s_nop 0
	global_load_dword v36, v[30:31], off offset:224
	global_load_dword v37, v[30:31], off offset:232
	global_load_dword v38, v[30:31], off offset:240
	v_add_co_u32_e32 v24, vcc, s91, v24
	s_add_u32 s30, s16, s22
	s_nop 0
	v_addc_co_u32_e32 v25, vcc, 0, v25, vcc
	global_load_dword v30, v[30:31], off offset:248
	s_nop 0
	global_load_dword v24, v[24:25], off nt
	s_addc_u32 s31, s23, s25
	s_waitcnt vmcnt(39)
	v_mul_f32_e32 v21, 0x42800000, v21
	v_mul_f32_e32 v9, v9, v21
	s_waitcnt vmcnt(38)
	v_mul_f32_e32 v21, 0x42800000, v71
	v_mul_f32_e32 v11, v11, v21
	s_waitcnt vmcnt(37)
	v_mul_f32_e32 v21, 0x42800000, v72
	v_mul_f32_e32 v13, v13, v21
	s_waitcnt vmcnt(36)
	v_mul_f32_e32 v21, 0x42800000, v73
	v_mul_f32_e32 v15, v15, v21
	s_waitcnt vmcnt(35)
	v_mul_f32_e32 v21, 0x42800000, v74
	v_mul_f32_e32 v17, v17, v21
	s_waitcnt vmcnt(34)
	v_mul_f32_e32 v21, 0x42800000, v75
	v_mul_f32_e32 v19, v19, v21
	s_waitcnt vmcnt(33)
	v_mul_f32_e32 v21, 0x42800000, v76
	v_mul_f32_e32 v21, v42, v21
	s_waitcnt vmcnt(32)
	v_mul_f32_e32 v25, 0x42800000, v77
	s_waitcnt vmcnt(27)
	v_mul_f32_e32 v42, 0x42800000, v82
	v_mul_f32_e32 v42, v48, v42
	v_mul_f32_e32 v31, 0x42800000, v78
	v_mul_f32_e32 v39, 0x42800000, v79
	v_mul_f32_e32 v40, 0x42800000, v80
	v_mul_f32_e32 v41, 0x42800000, v81
	v_mul_f32_e32 v25, v43, v25
	s_waitcnt vmcnt(21)
	v_mul_f32_e32 v48, 0x42800000, v88
	v_mul_f32_e32 v48, v65, v48
	s_waitcnt vmcnt(15)
	v_mul_f32_e32 v65, 0x42800000, v94
	v_mul_f32_e32 v31, v44, v31
	v_mul_f32_e32 v39, v45, v39
	v_mul_f32_e32 v40, v46, v40
	s_waitcnt vmcnt(5)
	v_mul_f32_e32 v35, 0x42800000, v35
	v_mul_f32_e32 v29, v29, v35
	s_waitcnt vmcnt(4)
	v_mul_f32_e32 v35, 0x42800000, v36
	v_mul_f32_e32 v41, v47, v41
	v_mul_f32_e32 v43, 0x42800000, v83
	v_mul_f32_e32 v44, 0x42800000, v84
	v_mul_f32_e32 v45, 0x42800000, v85
	v_mul_f32_e32 v46, 0x42800000, v86
	v_mul_f32_e32 v47, 0x42800000, v87
	v_mul_f32_e32 v26, v26, v65
	v_mul_f32_e32 v65, 0x42800000, v95
	v_mul_f32_e32 v32, v32, v35
	s_waitcnt vmcnt(3)
	v_mul_f32_e32 v35, 0x42800000, v37
	v_mul_f32_e32 v43, v49, v43
	v_mul_f32_e32 v44, v50, v44
	v_mul_f32_e32 v45, v51, v45
	v_mul_f32_e32 v46, v52, v46
	v_mul_f32_e32 v47, v53, v47
	v_mul_f32_e32 v49, 0x42800000, v89
	v_mul_f32_e32 v50, 0x42800000, v90
	v_mul_f32_e32 v51, 0x42800000, v91
	v_mul_f32_e32 v52, 0x42800000, v92
	v_mul_f32_e32 v53, 0x42800000, v93
	v_mul_f32_e32 v27, v27, v65
	v_mul_f32_e32 v65, 0x42800000, v96
	v_mul_f32_e32 v33, v33, v35
	s_waitcnt vmcnt(2)
	v_mul_f32_e32 v35, 0x42800000, v38
	s_waitcnt vmcnt(1)
	v_mul_f32_e32 v30, 0x42800000, v30
	v_mul_f32_e32 v49, v66, v49
	v_mul_f32_e32 v50, v67, v50
	v_mul_f32_e32 v51, v68, v51
	v_mul_f32_e32 v52, v69, v52
	v_mul_f32_e32 v53, v70, v53
	v_mul_f32_e32 v28, v28, v65
	v_mul_f32_e32 v34, v34, v35
	s_waitcnt vmcnt(0)
	v_mul_f32_e32 v24, v24, v30
	ds_write2_b32 v55, v9, v11 offset1:66
	ds_write2_b32 v55, v13, v15 offset0:132 offset1:198
	ds_write2_b32 v58, v17, v19 offset0:8 offset1:74
	ds_write2_b32 v58, v21, v25 offset0:140 offset1:206
	ds_write2_b32 v59, v31, v39 offset0:16 offset1:82
	ds_write2_b32 v59, v40, v41 offset0:148 offset1:214
	ds_write2_b32 v60, v42, v43 offset0:24 offset1:90
	ds_write2_b32 v60, v44, v45 offset0:156 offset1:222
	ds_write2_b32 v61, v46, v47 offset0:32 offset1:98
	ds_write2_b32 v61, v48, v49 offset0:164 offset1:230
	ds_write2_b32 v62, v50, v51 offset0:40 offset1:106
	ds_write2_b32 v62, v52, v53 offset0:172 offset1:238
	ds_write2_b32 v63, v26, v27 offset0:48 offset1:114
	ds_write2_b32 v63, v28, v29 offset0:180 offset1:246
	ds_write2_b32 v64, v32, v33 offset0:56 offset1:122
	ds_write2_b32 v64, v34, v24 offset0:188 offset1:254
	s_waitcnt lgkmcnt(0)
	v_add_u32_e32 v9, 0x800, v57
	ds_read2_b32 v[26:27], v57 offset1:33
	ds_read2_b32 v[30:31], v57 offset0:66 offset1:99
	ds_read2_b32 v[32:33], v9 offset0:16 offset1:49
	v_mov_b32_e32 v24, v3
	v_mov_b32_e32 v28, v3
	ds_read2_b32 v[34:35], v57 offset0:132 offset1:165
	s_waitcnt lgkmcnt(3)
	v_cvt_pk_fp8_f32 v24, v26, v27
	ds_read2_b32 v[26:27], v9 offset0:82 offset1:115
	s_waitcnt lgkmcnt(2)
	v_cvt_pk_fp8_f32 v28, v32, v33
	ds_read2_b32 v[32:33], v57 offset0:198 offset1:231
	ds_read2_b32 v[36:37], v9 offset0:148 offset1:181
	v_mov_b32_e32 v25, v3
	s_waitcnt lgkmcnt(3)
	v_cvt_pk_fp8_f32 v25, v34, v35
	ds_read2_b32 v[34:35], v9 offset0:214 offset1:247
	v_mov_b32_e32 v29, v3
	s_waitcnt lgkmcnt(1)
	v_cvt_pk_fp8_f32 v29, v36, v37
	v_add_u32_e32 v9, 0x400, v57
	v_add_u32_e32 v11, 0xc00, v57
	v_cvt_pk_fp8_f32 v24, v30, v31 op_sel:[0,0,1]
	v_cvt_pk_fp8_f32 v25, v32, v33 op_sel:[0,0,1]
	s_waitcnt lgkmcnt(0)
	v_cvt_pk_fp8_f32 v29, v34, v35 op_sel:[0,0,1]
	ds_read2_b32 v[30:31], v9 offset0:8 offset1:41
	ds_read2_b32 v[32:33], v9 offset0:74 offset1:107
	ds_read2_b32 v[34:35], v11 offset0:24 offset1:57
	v_cvt_pk_fp8_f32 v28, v26, v27 op_sel:[0,0,1]
	v_mov_b32_e32 v26, v3
	s_waitcnt lgkmcnt(2)
	v_cvt_pk_fp8_f32 v26, v30, v31
	v_mov_b32_e32 v30, v3
	ds_read2_b32 v[38:39], v9 offset0:140 offset1:173
	ds_read2_b32 v[36:37], v11 offset0:90 offset1:123
	s_waitcnt lgkmcnt(2)
	v_cvt_pk_fp8_f32 v30, v34, v35
	ds_read2_b32 v[34:35], v9 offset0:206 offset1:239
	ds_read2_b32 v[40:41], v11 offset0:156 offset1:189
	v_mov_b32_e32 v27, v3
	s_waitcnt lgkmcnt(3)
	v_cvt_pk_fp8_f32 v27, v38, v39
	ds_read2_b32 v[38:39], v11 offset0:222 offset1:255
	v_mov_b32_e32 v31, v3
	s_waitcnt lgkmcnt(1)
	v_cvt_pk_fp8_f32 v31, v40, v41
	v_cvt_pk_fp8_f32 v26, v32, v33 op_sel:[0,0,1]
	v_cvt_pk_fp8_f32 v27, v34, v35 op_sel:[0,0,1]
	v_lshl_add_u64 v[32:33], s[30:31], 0, v[6:7]
	v_cvt_pk_fp8_f32 v30, v36, v37 op_sel:[0,0,1]
	s_waitcnt lgkmcnt(0)
	v_cvt_pk_fp8_f32 v31, v38, v39 op_sel:[0,0,1]
	v_lshl_add_u64 v[32:33], v[32:33], 0, v[4:5]
	v_lshl_add_u64 v[34:35], v[32:33], 0, s[18:19]
	v_add_co_u32_e32 v32, vcc, 0xffb80000, v32
	s_mov_b64 s[30:31], 0
	s_nop 0
	v_addc_co_u32_e32 v33, vcc, -1, v33, vcc
	global_store_dwordx4 v[32:33], v[24:27], off sc1
	global_store_dwordx4 v[34:35], v[28:31], off offset:16 sc1
	s_waitcnt lgkmcnt(0)

.LBB0_49:
	v_ashrrev_i32_e32 v7, 31, v6
	v_lshl_add_u64 v[10:11], v[6:7], 2, s[12:13]
	global_load_dwordx2 v[10:11], v[10:11], off
	v_bfe_u32 v9, v8, 6, 7
	v_add_u32_e32 v8, s14, v8
	v_and_b32_e32 v7, 0x7e, v6
	v_cmp_lt_i32_e32 vcc, s20, v8
	s_or_b64 s[18:19], vcc, s[18:19]
	v_cmp_le_u32_e32 vcc, v7, v9
	v_cmp_lt_u32_e64 s[4:5], v7, v9
	v_add_u32_e32 v6, s15, v6
	s_waitcnt vmcnt(0)
	v_cndmask_b32_e32 v7, 0, v10, vcc
	v_cndmask_b32_e64 v9, 0, v11, s[4:5]
	v_cvt_pk_bf16_f32 v7, v7, v9
	global_store_dword v[4:5], v7, off sc1
	v_lshl_add_u64 v[4:5], v[4:5], 0, s[16:17]
	s_andn2_b64 exec, exec, s[18:19]
	s_cbranch_execnz .LBB0_49

.LBB0_52:
	v_ashrrev_i32_e32 v8, 13, v2
	v_bfe_u32 v12, v2, 6, 7
	v_ashrrev_i32_e32 v9, 31, v8
	v_and_b32_e32 v6, 0x3f00, v3
	v_lshl_or_b32 v10, v8, 7, v12
	v_lshlrev_b64 v[8:9], 16, v[8:9]
	v_lshlrev_b32_e32 v6, 2, v6
	v_ashrrev_i32_e32 v11, 31, v10
	v_lshl_add_u64 v[8:9], s[4:5], 0, v[8:9]
	v_lshl_add_u64 v[10:11], v[10:11], 2, s[6:7]
	v_lshl_add_u64 v[8:9], v[8:9], 0, v[6:7]
	v_lshlrev_b32_e32 v6, 2, v12
	global_load_dword v10, v[10:11], off
	v_lshl_add_u64 v[8:9], v[8:9], 0, v[6:7]
	global_load_dword v6, v[8:9], off
	global_load_dword v11, v[8:9], off offset:512
	v_add_u32_e32 v2, s14, v2
	v_cmp_lt_i32_e32 vcc, s18, v2
	v_add_u32_e32 v3, s15, v3
	s_or_b64 s[16:17], vcc, s[16:17]
	s_waitcnt vmcnt(1)
	v_mul_f32_e32 v6, v10, v6
	s_waitcnt vmcnt(0)
	v_mul_f32_e32 v8, v10, v11
	v_cvt_pk_bf16_f32 v6, v6, v8
	global_store_dword v[4:5], v6, off sc1
	v_lshl_add_u64 v[4:5], v[4:5], 0, s[10:11]
	s_andn2_b64 exec, exec, s[16:17]
	s_cbranch_execnz .LBB0_52

.LBB0_73:
	s_or_b64 exec, exec, s[6:7]
	v_cvt_f32_u32_e32 v6, v3
	s_waitcnt vmcnt(0)
	v_readfirstlane_b32 s6, v5
	v_sub_u32_e32 v5, 0, v3
	v_rcp_iflag_f32_e32 v6, v6
	v_add_u32_e32 v4, s6, v4
	v_mul_f32_e32 v6, 0x4f7ffffe, v6
	v_cvt_u32_f32_e32 v6, v6
	v_mul_lo_u32 v5, v5, v6
	v_mul_hi_u32 v5, v6, v5
	v_add_u32_e32 v5, v6, v5
	v_mul_hi_u32 v5, v4, v5
	v_mul_lo_u32 v6, v5, v3
	v_sub_u32_e32 v6, v4, v6
	v_add_u32_e32 v7, 1, v5
	v_cmp_ge_u32_e32 vcc, v6, v3
	s_nop 1
	v_cndmask_b32_e32 v5, v5, v7, vcc
	v_sub_u32_e32 v7, v6, v3
	v_cndmask_b32_e32 v6, v6, v7, vcc
	v_add_u32_e32 v7, 1, v5
	v_cmp_ge_u32_e32 vcc, v6, v3
	v_add_u32_e32 v6, 1, v4
	s_nop 0
	v_cndmask_b32_e32 v5, v5, v7, vcc
	v_add_u32_e32 v4, 1, v5
	v_mul_lo_u32 v3, v4, v3
	v_cmp_eq_u32_e32 vcc, v6, v3
	s_and_saveexec_b64 s[6:7], vcc
	s_cbranch_execz .LBB0_76
	s_mov_b64 s[8:9], exec
	v_mbcnt_lo_u32_b32 v3, s8, 0
	s_nop 0
	s_waitcnt lgkmcnt(0)
	s_waitcnt vmcnt(0)
	v_mbcnt_hi_u32_b32 v3, s9, v3
	v_cmp_eq_u32_e32 vcc, 0, v3
	s_and_b64 s[10:11], exec, vcc
	s_mov_b64 exec, s[10:11]
	s_cbranch_execz .LBB0_76
	s_bcnt1_i32_b64 s8, s[8:9]
	v_mov_b32_e32 v3, 0x3000
	v_mov_b32_e32 v5, s8
	global_atomic_add v3, v5, s[96:97] offset:1024
